# speedup vs baseline: 1.0195x; 1.0013x over previous
; #define LAS __attribute__((address_space(3)))
; __device__ __forceinline__ int opaque_tid() { int t; asm volatile("v_mov_b32 %0, %1" : "=v"(t) : "v"(threadIdx.x)); return t; }
; __device__ __forceinline__ int v_rd_base(int lane) { return ((lane & 3) << 3) | (((lane >> 2) & 3) << 6) | (((lane >> 4) & 1) << 5) | (((lane >> 5) & 1) << 8); }
; __device__ __forceinline__ void attn_body256(const bf16_t* __restrict__ Qb, const bf16_t* __restrict__ Kh, const bf16_t* __restrict__ Vh,
;                                              bf16_t* Ob, int seq, unsigned char* lds, float lam, int MODE, bf16_t* Ab, const float* wsub) {
;   const int tid = opaque_tid(), wid = __builtin_amdgcn_readfirstlane(tid >> 6), lane = tid & 63, r32 = lane & 31, hi = lane >> 5;
;   LAS unsigned char* ldsl = (LAS unsigned char*)lds;
;   float* ws = (float*)(lds + A2_WS) + wid * 64; float* li_l = ws; float* al_l = ws + 32;
;   unsigned koff[2], voff[4];
; #pragma unroll
;   for (int i = 0; i < 2; ++i) { const int o = i * 8192 + tid * 16; const int row = o >> 8; const int colB = (o & 255) ^ ((row & 7) << 4);
;     koff[i] = (unsigned)(row * LDK + (colB >> 1));
;     const int sub = o >> 9, kk = (sub >> 2) * 8 + ((o & 511) >> 6), c = (sub & 3) * 32 + (((o & 511) >> 1) & 31);
;     const int k = (kk & ~0xC) | ((kk & 4) << 1) | ((kk & 8) >> 1);
;     voff[i] = (unsigned)(k * LDK + c); voff[2 + i] = (unsigned)(k * LDK + 128 + c); }
;     ...
;   const int NT = seq / KVBLK;
;   A2_DMA(0, 0); A2_DMA(1, 1);
;   float m_reg = -1e30f, l_reg = 0; f32x16 o[8] = {}; bf16x8 qr[8];
;   const bf16_t* Qw = Qb + (long)(wid * QBLK + r32) * LDQ + hi * 8;
; #pragma unroll
;   for (int d0 = 0; d0 < 8; ++d0) qr[d0] = *reinterpret_cast<const bf16x8*>(Qw + d0 * 16);
;   const int vb0 = (int)(uintptr_t)lds + v_rd_base(lane);
;   asm volatile("s_waitcnt vmcnt(0)" ::: "memory"); __syncthreads();
.LBB0_669:
	s_and_b32 s2, s18, 1
	s_lshl_b64 s[10:11], s[62:63], 11
	s_lshl_b64 s[6:7], s[62:63], 12
	s_add_u32 s9, s96, s6
	s_addc_u32 s12, s97, s7
	s_lshl_b32 s16, s8, 8
	s_lshl_b32 s6, s2, 7
	s_or_b32 s6, s16, s6
	s_ashr_i32 s7, s6, 31
	s_lshl_b64 s[14:15], s[6:7], 1
	s_add_u32 s6, s9, s14
	s_addc_u32 s7, s12, s15
	s_lshl_b64 s[8:9], s[0:1], 1
	s_add_u32 s0, s60, s8
	s_addc_u32 s1, s53, s9
	s_add_u32 s12, s0, s14
	s_addc_u32 s13, s1, s15
	v_mov_b32 v16, v231
	v_lshrrev_b32_e32 v245, 7, v231
	v_lshlrev_b32_e32 v245, 3, v245
	v_bfe_u32 v244, v231, 1, 3
	v_add_u32_e32 v245, v245, v244
	v_lshlrev_b32_e32 v245, 11, v245
	v_bfe_u32 v244, v231, 4, 3
	v_lshl_add_u32 v245, v244, 4, v245
	v_and_b32_e32 v244, 1, v231
	v_lshl_add_u32 v245, v244, 3, v245
	v_lshrrev_b32_e32 v239, 4, v231
	v_and_b32_e32 v244, 15, v239
	v_and_b32_e32 v242, 15, v231
	v_xor_b32_e32 v242, v242, v244
	v_lshlrev_b32_e32 v242, 3, v242
	v_lshl_add_u32 v239, v239, 11, v242
	s_add_u32 s20, s61, s8
	v_lshlrev_b32_e32 v17, 4, v16
	v_add_u32_e32 v6, 0x2000, v17
	s_addc_u32 s21, s68, s9
	s_ashr_i32 s17, s16, 31
	v_ashrrev_i32_e32 v8, 8, v6
	s_lshl_b64 s[0:1], s[16:17], 1
	v_and_b32_e32 v3, 0xf0, v17
	v_lshlrev_b32_e32 v6, 4, v8
	s_movk_i32 s26, 0x70
	s_add_u32 s16, s20, s0
	v_lshrrev_b32_e32 v0, 1, v16
	v_ashrrev_i32_e32 v2, 4, v16
	v_bitop3_b32 v3, v6, v3, s26 bitop3:0x6c
	s_addc_u32 s17, s21, s1
	v_readfirstlane_b32 s20, v16
	v_and_b32_e32 v22, 8, v0
	v_and_b32_e32 v0, 0x70, v16
	s_movk_i32 s21, 0xf0
	v_lshrrev_b32_e32 v4, 1, v2
	v_lshrrev_b32_e32 v3, 1, v3
	s_ashr_i32 s23, s20, 6
	v_bfe_u32 v18, v16, 2, 2
	v_lshlrev_b32_e32 v20, 3, v16
	v_bitop3_b32 v0, v17, v0, s21 bitop3:0x6c
	v_and_b32_e32 v4, 4, v4
	v_lshl_or_b32 v6, v8, 11, v3
	v_add_u32_e32 v6, 0x10000, v239
	v_and_b32_e32 v3, 0x1ffff0, v8
	v_lshrrev_b32_e32 v8, 1, v8
	v_and_b32_e32 v19, 0x60, v16
	v_and_b32_e32 v21, 24, v20
	v_or_b32_e32 v7, v22, v18
	v_lshrrev_b32_e32 v0, 1, v0
	v_and_or_b32 v23, v2, -16, v4
	v_and_b32_e32 v8, 4, v8
	s_lshl_b32 s21, s23, 10
	v_or_b32_e32 v5, v21, v19
	v_lshl_or_b32 v0, v2, 11, v0
	v_mov_b32_e32 v0, v239
	v_or_b32_e32 v2, v7, v23
	v_or3_b32 v3, v3, v8, v7
	s_add_i32 s21, s21, 0
	v_lshl_or_b32 v2, v2, 11, v5
	v_mov_b32_e32 v2, v245
	v_lshlrev_b32_e32 v24, 11, v3
	s_add_i32 s22, s21, 0x10000
	v_lshlrev_b64 v[12:13], 1, v[0:1]
	v_mov_b32_e32 v3, v1
	v_or_b32_e32 v4, 0x80, v2
	v_lshl_add_u64 v[14:15], s[12:13], 0, v[12:13]
	s_mov_b32 m0, s22
	v_lshlrev_b64 v[2:3], 1, v[2:3]
	s_add_i32 s24, s21, 0x4000
	global_load_lds_dwordx4 v[14:15], off
	v_lshl_add_u64 v[14:15], s[16:17], 0, v[2:3]
	s_mov_b32 m0, s21
	s_mov_b64 s[30:31], 0x100
	v_mov_b32_e32 v7, v1
	s_and_b32 s20, s20, 0x3fffffc0
	v_or_b32_e32 v8, v24, v5
	v_add_u32_e32 v8, 0x10000, v245
	global_load_lds_dwordx4 v[14:15], off
	v_lshl_add_u64 v[14:15], v[14:15], 0, s[30:31]
	s_mov_b32 m0, s24
	v_lshlrev_b64 v[6:7], 1, v[6:7]
	v_mov_b32_e32 v9, v1
	s_lshl_b32 s20, s20, 2
	v_or_b32_e32 v10, 0x80, v8
	global_load_lds_dwordx4 v[14:15], off
	v_lshl_add_u64 v[14:15], s[12:13], 0, v[6:7]
	s_add_i32 m0, s21, 0x12000
	v_lshlrev_b64 v[8:9], 1, v[8:9]
	s_add_i32 s20, s20, 0
	global_load_lds_dwordx4 v[14:15], off
	v_lshl_add_u64 v[14:15], s[16:17], 0, v[8:9]
	s_add_i32 m0, s21, 0x2000
	s_add_i32 s20, s20, 0x18000
	global_load_lds_dwordx4 v[14:15], off
	s_add_i32 m0, s21, 0x6000
	s_add_u32 s12, s12, 0x40000
	s_addc_u32 s13, s13, 0
	v_lshl_add_u64 v[14:15], v[14:15], 0, s[30:31]
	s_add_u32 s16, s16, 0x40000
	global_load_lds_dwordx4 v[14:15], off
	s_addc_u32 s17, s17, 0
	s_add_i32 m0, s21, 0x14000
	s_add_i32 s24, s21, 0x8000
	v_lshl_add_u64 v[14:15], s[12:13], 0, v[12:13]
	v_mov_b32_e32 v5, v1
	s_add_i32 s25, s21, 0xc000
	global_load_lds_dwordx4 v[14:15], off
	v_lshl_add_u64 v[2:3], s[16:17], 0, v[2:3]
	s_mov_b32 m0, s24
	v_mov_b32_e32 v11, v1
	global_load_lds_dwordx4 v[2:3], off
	v_lshl_add_u64 v[2:3], v[4:5], 1, s[16:17]
	s_mov_b32 m0, s25
	v_and_b32_e32 v228, 31, v16
	global_load_lds_dwordx4 v[2:3], off
	v_lshl_add_u64 v[2:3], s[12:13], 0, v[6:7]
	s_add_i32 m0, s21, 0x16000
	s_lshl_b32 s12, s23, 5
	global_load_lds_dwordx4 v[2:3], off
	v_lshl_add_u64 v[2:3], s[16:17], 0, v[8:9]
	s_add_i32 m0, s21, 0xa000
	v_bfe_u32 v229, v16, 5, 1
	global_load_lds_dwordx4 v[2:3], off
	v_lshl_add_u64 v[2:3], v[10:11], 1, s[16:17]
	s_add_i32 m0, s21, 0xe000
	v_lshlrev_b32_e32 v0, 4, v229
	global_load_lds_dwordx4 v[2:3], off
	v_and_b32_e32 v2, 15, v231
	v_or_b32_e32 v2, s12, v2
	v_mov_b32_e32 v3, 0
	v_lshlrev_b64 v[2:3], 12, v[2:3]
	v_lshl_add_u64 v[2:3], s[6:7], 0, v[2:3]
	v_bfe_u32 v194, v231, 4, 2
	v_lshlrev_b32_e32 v194, 4, v194
	v_mov_b32_e32 v195, 0
	v_lshl_add_u64 v[2:3], v[2:3], 0, v[194:195]
	global_load_dwordx4 v[162:165], v[2:3], off
	global_load_dwordx4 v[166:169], v[2:3], off offset:64
	global_load_dwordx4 v[170:173], v[2:3], off offset:128
	global_load_dwordx4 v[174:177], v[2:3], off offset:192
	v_mov_b32_e32 v194, 0x10000
	v_lshl_add_u64 v[2:3], v[2:3], 0, v[194:195]
	global_load_dwordx4 v[178:181], v[2:3], off
	global_load_dwordx4 v[182:185], v[2:3], off offset:64
	global_load_dwordx4 v[186:189], v[2:3], off offset:128
	global_load_dwordx4 v[190:193], v[2:3], off offset:192
	v_and_b32_e32 v8, 0x70, v17
	s_movk_i32 s6, 0x60
	v_bitop3_b32 v236, v0, v8, s6 bitop3:0x36
	s_movk_i32 s6, 0x80
	v_bitop3_b32 v237, v0, v8, s6 bitop3:0x36
	s_movk_i32 s6, 0xa0
	v_bitop3_b32 v240, v0, v8, s6 bitop3:0x36
	s_movk_i32 s6, 0xc0
	s_cmp_lg_u32 0, -1
	v_and_b32_e32 v2, 63, v16
	v_lshlrev_b32_e32 v3, 1, v16
	v_and_b32_e32 v4, 0x118, v20
	v_bitop3_b32 v241, v0, v8, s6 bitop3:0x36
	s_movk_i32 s6, 0xe0
	s_cselect_b32 s16, 0, 0
	s_lshl_b32 s23, s19, 18
	v_and_b32_e32 v5, 0xc0, v17
	v_bitop3_b32 v247, v0, v8, s6 bitop3:0x36
	v_cmp_gt_u32_e64 s[6:7], 32, v2
	v_and_or_b32 v2, v3, 32, v4
	s_add_u32 s14, s8, s14
	v_add3_u32 v248, v5, s16, v2
	s_addc_u32 s15, s9, s15
	v_readlane_b32 s16, v254, 41
	s_add_u32 s14, s16, s14
	v_readlane_b32 s16, v254, 42
	s_addc_u32 s15, s16, s15
	s_add_u32 s8, s8, s0
	s_addc_u32 s9, s9, s1
	v_or3_b32 v2, v23, v22, v18
	v_lshlrev_b32_e32 v2, 11, v2
	s_add_u32 s8, s88, s8
	v_or3_b32 v2, v2, v19, v21
	v_mov_b32_e32 v2, v245
	v_mov_b32_e32 v3, v1
	s_addc_u32 s9, s89, s9
	s_waitcnt vmcnt(0)
; __device__ __forceinline__ void attn_body256(const bf16_t* __restrict__ Qb, const bf16_t* __restrict__ Kh, const bf16_t* __restrict__ Vh,
;                                              bf16_t* Ob, int seq, unsigned char* lds, float lam, int MODE, bf16_t* Ab, const float* wsub) {
;     ...
;   unsigned koff[2], voff[4];
; #pragma unroll
;   for (int i = 0; i < 2; ++i) { const int o = i * 8192 + tid * 16; const int row = o >> 8; const int colB = (o & 255) ^ ((row & 7) << 4);
;     koff[i] = (unsigned)(row * LDK + (colB >> 1));
;     const int sub = o >> 9, kk = (sub >> 2) * 8 + ((o & 511) >> 6), c = (sub & 3) * 32 + (((o & 511) >> 1) & 31);
;     const int k = (kk & ~0xC) | ((kk & 4) << 1) | ((kk & 8) >> 1);
;     voff[i] = (unsigned)(k * LDK + c); voff[2 + i] = (unsigned)(k * LDK + 128 + c); }
;     ...
;   const int NT = seq / KVBLK;
;   A2_DMA(0, 0); A2_DMA(1, 1);
;   float m_reg = -1e30f, l_reg = 0; f32x16 o[8] = {}; bf16x8 qr[8];
	v_bitop3_b32 v232, v0, v17, s26 bitop3:0x78
	v_lshl_add_u64 v[224:225], v[2:3], 1, s[8:9]
	s_add_u32 s66, s8, 0x25480000
	s_addc_u32 s67, s9, 0
	v_or3_b32 v2, v24, v19, v21
	v_add_u32_e32 v2, 0x10000, v245
	v_mov_b32_e32 v16, v1
	v_mov_b32_e32 v17, v1
	v_bitop3_b32 v233, v0, v8, 32 bitop3:0x36
	v_bitop3_b32 v234, v0, v8, 64 bitop3:0x36
	v_lshl_add_u64 v[220:221], s[14:15], 0, v[12:13]
	v_lshl_add_u64 v[222:223], s[14:15], 0, v[6:7]
	v_lshl_add_u64 v[226:227], v[2:3], 1, s[8:9]
	v_mov_b32_e32 v2, v1
	v_mov_b32_e32 v4, v1
	v_mov_b32_e32 v5, v1
	v_mov_b32_e32 v6, v1
	v_mov_b32_e32 v7, v1
	v_mov_b32_e32 v8, v1
	v_mov_b32_e32 v9, v1
	v_mov_b32_e32 v10, v1
	v_mov_b32_e32 v12, v1
	v_mov_b32_e32 v13, v1
	v_mov_b32_e32 v14, v1
	v_mov_b32_e32 v15, v1
	v_mov_b64_e32 v[128:129], v[16:17]
	v_mov_b64_e32 v[112:113], v[16:17]
	v_mov_b64_e32 v[96:97], v[16:17]
	v_mov_b64_e32 v[80:81], v[16:17]
	v_mov_b64_e32 v[64:65], v[16:17]
	v_mov_b64_e32 v[48:49], v[16:17]
	v_mov_b64_e32 v[32:33], v[16:17]
	s_mov_b32 s13, 2
	v_lshlrev_b32_e32 v230, 8, v228
	v_lshl_add_u32 v238, v228, 2, s20
	v_mov_b32_e32 v250, 0
	v_mov_b32_e32 v249, 0xf149f2ca
	s_nop 0
	v_mov_b64_e32 v[126:127], v[14:15]
	v_mov_b64_e32 v[124:125], v[12:13]
	v_mov_b64_e32 v[122:123], v[10:11]
	v_mov_b64_e32 v[120:121], v[8:9]
	v_mov_b64_e32 v[118:119], v[6:7]
	v_mov_b64_e32 v[116:117], v[4:5]
	v_mov_b64_e32 v[114:115], v[2:3]
	v_mov_b64_e32 v[110:111], v[14:15]
	v_mov_b64_e32 v[108:109], v[12:13]
	v_mov_b64_e32 v[106:107], v[10:11]
	v_mov_b64_e32 v[104:105], v[8:9]
	v_mov_b64_e32 v[102:103], v[6:7]
	v_mov_b64_e32 v[100:101], v[4:5]
	v_mov_b64_e32 v[98:99], v[2:3]
	v_mov_b64_e32 v[94:95], v[14:15]
	v_mov_b64_e32 v[92:93], v[12:13]
	v_mov_b64_e32 v[90:91], v[10:11]
	v_mov_b64_e32 v[88:89], v[8:9]
	v_mov_b64_e32 v[86:87], v[6:7]
	v_mov_b64_e32 v[84:85], v[4:5]
	v_mov_b64_e32 v[82:83], v[2:3]
	v_mov_b64_e32 v[78:79], v[14:15]
	v_mov_b64_e32 v[76:77], v[12:13]
	v_mov_b64_e32 v[74:75], v[10:11]
	v_mov_b64_e32 v[72:73], v[8:9]
	v_mov_b64_e32 v[70:71], v[6:7]
	v_mov_b64_e32 v[68:69], v[4:5]
	v_mov_b64_e32 v[66:67], v[2:3]
	v_mov_b64_e32 v[62:63], v[14:15]
	v_mov_b64_e32 v[60:61], v[12:13]
	v_mov_b64_e32 v[58:59], v[10:11]
	v_mov_b64_e32 v[56:57], v[8:9]
	v_mov_b64_e32 v[54:55], v[6:7]
	v_mov_b64_e32 v[52:53], v[4:5]
	v_mov_b64_e32 v[50:51], v[2:3]
	v_mov_b64_e32 v[46:47], v[14:15]
	v_mov_b64_e32 v[44:45], v[12:13]
	v_mov_b64_e32 v[42:43], v[10:11]
	v_mov_b64_e32 v[40:41], v[8:9]
	v_mov_b64_e32 v[38:39], v[6:7]
	v_mov_b64_e32 v[36:37], v[4:5]
	v_mov_b64_e32 v[34:35], v[2:3]
	v_mov_b64_e32 v[30:31], v[14:15]
	v_mov_b64_e32 v[28:29], v[12:13]
	v_mov_b64_e32 v[26:27], v[10:11]
	v_mov_b64_e32 v[24:25], v[8:9]
	v_mov_b64_e32 v[22:23], v[6:7]
	v_mov_b64_e32 v[20:21], v[4:5]
	v_mov_b64_e32 v[18:19], v[2:3]
	v_and_b32_e32 v237, 15, v231
	v_bfe_u32 v240, v231, 4, 2
	v_add_u32_e32 v247, 0, v240
	v_xor_b32_e32 v247, v247, v237
	v_lshlrev_b32_e32 v247, 4, v247
	v_lshl_add_u32 v232, v237, 8, v247
	v_add_u32_e32 v247, 4, v240
	v_xor_b32_e32 v247, v247, v237
	v_lshlrev_b32_e32 v247, 4, v247
	v_lshl_add_u32 v233, v237, 8, v247
	v_add_u32_e32 v247, 8, v240
	v_xor_b32_e32 v247, v247, v237
	v_lshlrev_b32_e32 v247, 4, v247
	v_lshl_add_u32 v246, v237, 8, v247
	v_add_u32_e32 v247, 12, v240
	v_xor_b32_e32 v247, v247, v237
	v_lshlrev_b32_e32 v247, 4, v247
	v_lshl_add_u32 v249, v237, 8, v247
	v_and_b32_e32 v247, 1, v240
	v_lshlrev_b32_e32 v248, 7, v247
	v_lshrrev_b32_e32 v247, 1, v240
	v_lshl_add_u32 v248, v247, 11, v248
	v_bfe_u32 v247, v231, 2, 2
	v_lshl_add_u32 v248, v247, 5, v248
	v_and_b32_e32 v247, 3, v231
	v_lshl_add_u32 v248, v247, 3, v248
	v_mov_b32_e32 v250, 0
	v_mov_b32_e32 v234, 0
	v_lshlrev_b32_e32 v220, 1, v239
	v_add_u32_e32 v221, 0x20000, v220
	v_lshlrev_b32_e32 v222, 1, v245
	v_add_u32_e32 v223, 0x20000, v222
	s_add_i32 s23, s19, 2
	v_mov_b32_e32 v236, 0
	v_mov_b32_e32 v237, 0
	v_mov_b32_e32 v238, 0
	v_mov_b32_e32 v239, 0
	v_mov_b32_e32 v240, 0
	v_mov_b32_e32 v241, 0
	v_mov_b32_e32 v242, 0
	v_mov_b32_e32 v243, 0
	s_movk_i32 s62, 0x7fff
	s_waitcnt vmcnt(0) lgkmcnt(0)
	s_barrier
	s_mov_b32 s98, 0
	s_mov_b32 s99, 0x8000
	s_mov_b32 s100, 0x19000
	s_cmpk_ge_u32 s21, 0x1000
	s_cbranch_scc1 .Lat_y_qk
	s_mov_b32 s9, 0x10000
	v_add_u32_e32 v230, s9, v232
	v_add_u32_e32 v247, s9, v233
	v_add_u32_e32 v228, s9, v246
	v_add_u32_e32 v245, s9, v249
	ds_read_b128 v[194:197], v230
	ds_read_b128 v[198:201], v230 offset:4096
	ds_read_b128 v[202:205], v230 offset:8192
	ds_read_b128 v[206:209], v230 offset:12288
	ds_read_b128 v[210:213], v247
	ds_read_b128 v[214:217], v247 offset:4096

; #define SBAR() __builtin_amdgcn_sched_barrier(0)
; #define PV_STEP(B) do { pv_reads<(B) + 1>(fn, vb); asm volatile("s_waitcnt lgkmcnt(8)" ::: "memory"); SBAR(); pv_mma(o[B], fc, pa0, pa1, pa2, pa3); SBAR(); fc = fn; } while (0)
; __device__ __forceinline__ void partialSM(f32x16& p0, f32x16& p1, float& m_reg, float& mn, float& alpha) {
;     ...
;   for (int r = 0; r < 16; ++r) p0[r] = __builtin_amdgcn_exp2f(p0[r]);
; }
; __device__ __forceinline__ void finishSM(f32x16& p0, f32x16& p1, float alpha, float& l_reg, bf16x8& pa0, bf16x8& pa1, bf16x8& pa2, bf16x8& pa3) {
;   for (int r = 0; r < 16; ++r) p1[r] = __builtin_amdgcn_exp2f(p1[r]);
;   float ps = 0; for (int r = 0; r < 16; ++r) ps += p0[r]; for (int r = 0; r < 16; ++r) ps += p1[r];
;   { auto rr = __builtin_amdgcn_permlane32_swap(__float_as_uint(ps), __float_as_uint(ps), false, false);
;     ps = __uint_as_float(rr[0]) + __uint_as_float(rr[1]); }
;   l_reg = l_reg * alpha + ps;
;     ...
;   PK4(p0, 0, pa0); PK4(p0, 8, pa1); PK4(p1, 0, pa2); PK4(p1, 8, pa3);
; __device__ __forceinline__ void pv_all(f32x16* o, int vb, bf16x8 pa0, bf16x8 pa1, bf16x8 pa2, bf16x8 pa3) {
;   VFrag fc, fn;
;   pv_reads<0>(fc, vb);
;   PV_STEP(0); PV_STEP(1); PV_STEP(2); PV_STEP(3); PV_STEP(4); PV_STEP(5); PV_STEP(6);
;   asm volatile("s_waitcnt lgkmcnt(0)" ::: "memory"); SBAR(); pv_mma(o[7], fc, pa0, pa1, pa2, pa3);
; }
.Lat_x_noresc:
	v_exp_f32_e32 v130, v130
	v_exp_f32_e32 v131, v131
	v_exp_f32_e32 v132, v132
	v_exp_f32_e32 v133, v133
	v_exp_f32_e32 v134, v134
	v_exp_f32_e32 v135, v135
	v_exp_f32_e32 v136, v136
	v_exp_f32_e32 v137, v137
	v_exp_f32_e32 v138, v138
	v_exp_f32_e32 v139, v139
	v_exp_f32_e32 v140, v140
	v_exp_f32_e32 v141, v141
	v_exp_f32_e32 v142, v142
	v_exp_f32_e32 v143, v143
	v_exp_f32_e32 v144, v144
	v_exp_f32_e32 v145, v145
	v_exp_f32_e32 v146, v146
	v_exp_f32_e32 v147, v147
	v_exp_f32_e32 v148, v148
	v_exp_f32_e32 v149, v149
	v_exp_f32_e32 v150, v150
	v_exp_f32_e32 v151, v151
	v_exp_f32_e32 v152, v152
	v_exp_f32_e32 v153, v153
	v_exp_f32_e32 v154, v154
	v_exp_f32_e32 v155, v155
	v_exp_f32_e32 v156, v156
	v_exp_f32_e32 v157, v157
	v_exp_f32_e32 v158, v158
	v_exp_f32_e32 v159, v159
	v_exp_f32_e32 v160, v160
	v_exp_f32_e32 v161, v161
	v_add_f32_e32 v194, v130, v131
	v_add_f32_e32 v194, v194, v132
	v_add_f32_e32 v194, v194, v133
	v_add_f32_e32 v194, v194, v138
	v_add_f32_e32 v194, v194, v139
	v_add_f32_e32 v194, v194, v140
	v_add_f32_e32 v194, v194, v141
	v_add_f32_e32 v194, v194, v146
	v_add_f32_e32 v194, v194, v147
	v_add_f32_e32 v194, v194, v148
	v_add_f32_e32 v194, v194, v149
	v_add_f32_e32 v194, v194, v154
	v_add_f32_e32 v194, v194, v155
	v_add_f32_e32 v194, v194, v156
	v_add_f32_e32 v194, v194, v157
	v_add_f32_e32 v195, v134, v135
	v_add_f32_e32 v195, v195, v136
	v_add_f32_e32 v195, v195, v137
	v_add_f32_e32 v195, v195, v142
	v_add_f32_e32 v195, v195, v143
	v_add_f32_e32 v195, v195, v144
	v_add_f32_e32 v195, v195, v145
	v_add_f32_e32 v195, v195, v150
	v_add_f32_e32 v195, v195, v151
	v_add_f32_e32 v195, v195, v152
	v_add_f32_e32 v195, v195, v153
	v_add_f32_e32 v195, v195, v158
	v_add_f32_e32 v195, v195, v159
	v_add_f32_e32 v195, v195, v160
	v_add_f32_e32 v195, v195, v161
	v_add_f32_e32 v250, v250, v194
	v_add_f32_e32 v234, v234, v195
	v_cvt_pk_bf16_f32 v130, v130, v131
	v_cvt_pk_bf16_f32 v131, v132, v133
	v_cvt_pk_bf16_f32 v132, v138, v139
	v_cvt_pk_bf16_f32 v133, v140, v141
	v_cvt_pk_bf16_f32 v134, v134, v135
	v_cvt_pk_bf16_f32 v135, v136, v137
	v_cvt_pk_bf16_f32 v136, v142, v143
	v_cvt_pk_bf16_f32 v137, v144, v145
	v_cvt_pk_bf16_f32 v138, v146, v147
	v_cvt_pk_bf16_f32 v139, v148, v149
	v_cvt_pk_bf16_f32 v140, v154, v155
	v_cvt_pk_bf16_f32 v141, v156, v157
	v_cvt_pk_bf16_f32 v142, v150, v151
	v_cvt_pk_bf16_f32 v143, v152, v153
	v_cvt_pk_bf16_f32 v144, v158, v159
	v_cvt_pk_bf16_f32 v145, v160, v161
	v_add_u32_e32 v244, s98, v248
	ds_read_b64_tr_b16 v[146:147], v244
	ds_read_b64_tr_b16 v[148:149], v244 offset:4096
	ds_read_b64_tr_b16 v[150:151], v244 offset:8192
	ds_read_b64_tr_b16 v[152:153], v244 offset:12288
	ds_read_b64_tr_b16 v[154:155], v244 offset:256
	ds_read_b64_tr_b16 v[156:157], v244 offset:4352
	ds_read_b64_tr_b16 v[158:159], v244 offset:8448
	ds_read_b64_tr_b16 v[160:161], v244 offset:12544
	ds_read_b64_tr_b16 v[194:195], v244 offset:512
	ds_read_b64_tr_b16 v[196:197], v244 offset:4608
	ds_read_b64_tr_b16 v[198:199], v244 offset:8704
	ds_read_b64_tr_b16 v[200:201], v244 offset:12800
	s_waitcnt lgkmcnt(8)
	v_mfma_f32_16x16x32_bf16 v[2:5], v[146:149], v[130:133], v[2:5]
	v_mfma_f32_16x16x32_bf16 v[6:9], v[146:149], v[134:137], v[6:9]
	v_mfma_f32_16x16x32_bf16 v[2:5], v[150:153], v[138:141], v[2:5]
	v_mfma_f32_16x16x32_bf16 v[6:9], v[150:153], v[142:145], v[6:9]
	ds_read_b64_tr_b16 v[146:147], v244 offset:768
	ds_read_b64_tr_b16 v[148:149], v244 offset:4864
	ds_read_b64_tr_b16 v[150:151], v244 offset:8960
	ds_read_b64_tr_b16 v[152:153], v244 offset:13056
	s_waitcnt lgkmcnt(8)
	v_mfma_f32_16x16x32_bf16 v[10:13], v[154:157], v[130:133], v[10:13]
	v_mfma_f32_16x16x32_bf16 v[14:17], v[154:157], v[134:137], v[14:17]
	v_mfma_f32_16x16x32_bf16 v[10:13], v[158:161], v[138:141], v[10:13]
	v_mfma_f32_16x16x32_bf16 v[14:17], v[158:161], v[142:145], v[14:17]
	ds_read_b64_tr_b16 v[154:155], v244 offset:1024
	ds_read_b64_tr_b16 v[156:157], v244 offset:5120
	ds_read_b64_tr_b16 v[158:159], v244 offset:9216
	ds_read_b64_tr_b16 v[160:161], v244 offset:13312
	s_waitcnt lgkmcnt(8)
	v_mfma_f32_16x16x32_bf16 v[114:117], v[194:197], v[130:133], v[114:117]
	v_mfma_f32_16x16x32_bf16 v[118:121], v[194:197], v[134:137], v[118:121]
	v_mfma_f32_16x16x32_bf16 v[114:117], v[198:201], v[138:141], v[114:117]
	v_mfma_f32_16x16x32_bf16 v[118:121], v[198:201], v[142:145], v[118:121]
	ds_read_b64_tr_b16 v[194:195], v244 offset:1280
	ds_read_b64_tr_b16 v[196:197], v244 offset:5376
	ds_read_b64_tr_b16 v[198:199], v244 offset:9472
	ds_read_b64_tr_b16 v[200:201], v244 offset:13568
	s_waitcnt lgkmcnt(8)
	v_mfma_f32_16x16x32_bf16 v[122:125], v[146:149], v[130:133], v[122:125]
	v_mfma_f32_16x16x32_bf16 v[126:129], v[146:149], v[134:137], v[126:129]
	v_mfma_f32_16x16x32_bf16 v[122:125], v[150:153], v[138:141], v[122:125]
	v_mfma_f32_16x16x32_bf16 v[126:129], v[150:153], v[142:145], v[126:129]
	ds_read_b64_tr_b16 v[146:147], v244 offset:1536
	ds_read_b64_tr_b16 v[148:149], v244 offset:5632
	ds_read_b64_tr_b16 v[150:151], v244 offset:9728
	ds_read_b64_tr_b16 v[152:153], v244 offset:13824
	s_waitcnt lgkmcnt(8)
	v_mfma_f32_16x16x32_bf16 v[98:101], v[154:157], v[130:133], v[98:101]
	v_mfma_f32_16x16x32_bf16 v[102:105], v[154:157], v[134:137], v[102:105]
	v_mfma_f32_16x16x32_bf16 v[98:101], v[158:161], v[138:141], v[98:101]
	v_mfma_f32_16x16x32_bf16 v[102:105], v[158:161], v[142:145], v[102:105]
	ds_read_b64_tr_b16 v[154:155], v244 offset:1792
	ds_read_b64_tr_b16 v[156:157], v244 offset:5888
	ds_read_b64_tr_b16 v[158:159], v244 offset:9984
	ds_read_b64_tr_b16 v[160:161], v244 offset:14080
	s_waitcnt lgkmcnt(8)
; #define SBAR() __builtin_amdgcn_sched_barrier(0)
; #define PV_STEP(B) do { pv_reads<(B) + 1>(fn, vb); asm volatile("s_waitcnt lgkmcnt(8)" ::: "memory"); SBAR(); pv_mma(o[B], fc, pa0, pa1, pa2, pa3); SBAR(); fc = fn; } while (0)
; __device__ __forceinline__ void pv_all(f32x16* o, int vb, bf16x8 pa0, bf16x8 pa1, bf16x8 pa2, bf16x8 pa3) {
;   VFrag fc, fn;
;   pv_reads<0>(fc, vb);
;   PV_STEP(0); PV_STEP(1); PV_STEP(2); PV_STEP(3); PV_STEP(4); PV_STEP(5); PV_STEP(6);
;   asm volatile("s_waitcnt lgkmcnt(0)" ::: "memory"); SBAR(); pv_mma(o[7], fc, pa0, pa1, pa2, pa3);
; }
; __device__ __forceinline__ void attn_body256(const bf16_t* __restrict__ Qb, const bf16_t* __restrict__ Kh, const bf16_t* __restrict__ Vh,
;                                              bf16_t* Ob, int seq, unsigned char* lds, float lam, int MODE, bf16_t* Ab, const float* wsub) {
;     ...
;     pv_all(o, vb0 + b * A2_VBUF, pa0, pa1, pa2, pa3);
;     asm volatile("s_waitcnt vmcnt(0)" ::: "memory"); __syncthreads();
;     if (j + 2 < NT) A2_DMA(j + 2, b);
	v_mfma_f32_16x16x32_bf16 v[106:109], v[194:197], v[130:133], v[106:109]
	v_mfma_f32_16x16x32_bf16 v[110:113], v[194:197], v[134:137], v[110:113]
	v_mfma_f32_16x16x32_bf16 v[106:109], v[198:201], v[138:141], v[106:109]
	v_mfma_f32_16x16x32_bf16 v[110:113], v[198:201], v[142:145], v[110:113]
	ds_read_b64_tr_b16 v[194:195], v244 offset:16384
	ds_read_b64_tr_b16 v[196:197], v244 offset:20480
	ds_read_b64_tr_b16 v[198:199], v244 offset:24576
	ds_read_b64_tr_b16 v[200:201], v244 offset:28672
	s_waitcnt lgkmcnt(8)
	v_mfma_f32_16x16x32_bf16 v[82:85], v[146:149], v[130:133], v[82:85]
	v_mfma_f32_16x16x32_bf16 v[86:89], v[146:149], v[134:137], v[86:89]
	v_mfma_f32_16x16x32_bf16 v[82:85], v[150:153], v[138:141], v[82:85]
	v_mfma_f32_16x16x32_bf16 v[86:89], v[150:153], v[142:145], v[86:89]
	ds_read_b64_tr_b16 v[146:147], v244 offset:16640
	ds_read_b64_tr_b16 v[148:149], v244 offset:20736
	ds_read_b64_tr_b16 v[150:151], v244 offset:24832
	ds_read_b64_tr_b16 v[152:153], v244 offset:28928
	s_waitcnt lgkmcnt(8)
	v_mfma_f32_16x16x32_bf16 v[90:93], v[154:157], v[130:133], v[90:93]
	v_mfma_f32_16x16x32_bf16 v[94:97], v[154:157], v[134:137], v[94:97]
	v_mfma_f32_16x16x32_bf16 v[90:93], v[158:161], v[138:141], v[90:93]
	v_mfma_f32_16x16x32_bf16 v[94:97], v[158:161], v[142:145], v[94:97]
	ds_read_b64_tr_b16 v[154:155], v244 offset:16896
	ds_read_b64_tr_b16 v[156:157], v244 offset:20992
	ds_read_b64_tr_b16 v[158:159], v244 offset:25088
	ds_read_b64_tr_b16 v[160:161], v244 offset:29184
	s_waitcnt lgkmcnt(8)
	v_mfma_f32_16x16x32_bf16 v[66:69], v[194:197], v[130:133], v[66:69]
	v_mfma_f32_16x16x32_bf16 v[70:73], v[194:197], v[134:137], v[70:73]
	v_mfma_f32_16x16x32_bf16 v[66:69], v[198:201], v[138:141], v[66:69]
	v_mfma_f32_16x16x32_bf16 v[70:73], v[198:201], v[142:145], v[70:73]
	ds_read_b64_tr_b16 v[194:195], v244 offset:17152
	ds_read_b64_tr_b16 v[196:197], v244 offset:21248
	ds_read_b64_tr_b16 v[198:199], v244 offset:25344
	ds_read_b64_tr_b16 v[200:201], v244 offset:29440
	s_waitcnt lgkmcnt(8)
	v_mfma_f32_16x16x32_bf16 v[74:77], v[146:149], v[130:133], v[74:77]
	v_mfma_f32_16x16x32_bf16 v[78:81], v[146:149], v[134:137], v[78:81]
	v_mfma_f32_16x16x32_bf16 v[74:77], v[150:153], v[138:141], v[74:77]
	v_mfma_f32_16x16x32_bf16 v[78:81], v[150:153], v[142:145], v[78:81]
	ds_read_b64_tr_b16 v[146:147], v244 offset:17408
	ds_read_b64_tr_b16 v[148:149], v244 offset:21504
	ds_read_b64_tr_b16 v[150:151], v244 offset:25600
	ds_read_b64_tr_b16 v[152:153], v244 offset:29696
	s_waitcnt lgkmcnt(8)
	v_mfma_f32_16x16x32_bf16 v[50:53], v[154:157], v[130:133], v[50:53]
	v_mfma_f32_16x16x32_bf16 v[54:57], v[154:157], v[134:137], v[54:57]
	v_mfma_f32_16x16x32_bf16 v[50:53], v[158:161], v[138:141], v[50:53]
	v_mfma_f32_16x16x32_bf16 v[54:57], v[158:161], v[142:145], v[54:57]
	ds_read_b64_tr_b16 v[154:155], v244 offset:17664
	ds_read_b64_tr_b16 v[156:157], v244 offset:21760
	ds_read_b64_tr_b16 v[158:159], v244 offset:25856
	ds_read_b64_tr_b16 v[160:161], v244 offset:29952
	s_waitcnt lgkmcnt(8)
	v_mfma_f32_16x16x32_bf16 v[58:61], v[194:197], v[130:133], v[58:61]
	v_mfma_f32_16x16x32_bf16 v[62:65], v[194:197], v[134:137], v[62:65]
	v_mfma_f32_16x16x32_bf16 v[58:61], v[198:201], v[138:141], v[58:61]
	v_mfma_f32_16x16x32_bf16 v[62:65], v[198:201], v[142:145], v[62:65]
	ds_read_b64_tr_b16 v[194:195], v244 offset:17920
	ds_read_b64_tr_b16 v[196:197], v244 offset:22016
	ds_read_b64_tr_b16 v[198:199], v244 offset:26112
	ds_read_b64_tr_b16 v[200:201], v244 offset:30208
	s_waitcnt lgkmcnt(8)
	v_mfma_f32_16x16x32_bf16 v[34:37], v[146:149], v[130:133], v[34:37]
	v_mfma_f32_16x16x32_bf16 v[38:41], v[146:149], v[134:137], v[38:41]
	v_mfma_f32_16x16x32_bf16 v[34:37], v[150:153], v[138:141], v[34:37]
	v_mfma_f32_16x16x32_bf16 v[38:41], v[150:153], v[142:145], v[38:41]
	ds_read_b64_tr_b16 v[146:147], v244 offset:18176
	ds_read_b64_tr_b16 v[148:149], v244 offset:22272
	ds_read_b64_tr_b16 v[150:151], v244 offset:26368
	ds_read_b64_tr_b16 v[152:153], v244 offset:30464
	s_waitcnt lgkmcnt(8)
	v_mfma_f32_16x16x32_bf16 v[42:45], v[154:157], v[130:133], v[42:45]
	v_mfma_f32_16x16x32_bf16 v[46:49], v[154:157], v[134:137], v[46:49]
	v_mfma_f32_16x16x32_bf16 v[42:45], v[158:161], v[138:141], v[42:45]
	v_mfma_f32_16x16x32_bf16 v[46:49], v[158:161], v[142:145], v[46:49]
	s_waitcnt lgkmcnt(4)
	v_mfma_f32_16x16x32_bf16 v[18:21], v[194:197], v[130:133], v[18:21]
	v_mfma_f32_16x16x32_bf16 v[22:25], v[194:197], v[134:137], v[22:25]
	v_mfma_f32_16x16x32_bf16 v[18:21], v[198:201], v[138:141], v[18:21]
	v_mfma_f32_16x16x32_bf16 v[22:25], v[198:201], v[142:145], v[22:25]
	s_waitcnt lgkmcnt(0)
	v_mfma_f32_16x16x32_bf16 v[26:29], v[146:149], v[130:133], v[26:29]
	v_mfma_f32_16x16x32_bf16 v[30:33], v[146:149], v[134:137], v[30:33]
	v_mfma_f32_16x16x32_bf16 v[26:29], v[150:153], v[138:141], v[26:29]
	v_mfma_f32_16x16x32_bf16 v[30:33], v[150:153], v[142:145], v[30:33]
	s_waitcnt vmcnt(0)
	s_barrier
	s_xor_b32 s9, s25, 1
	s_lshl_b32 s9, s9, 14
	s_add_i32 s9, s9, 0x10000
	v_add_u32_e32 v230, s9, v232
	v_add_u32_e32 v247, s9, v233
	v_add_u32_e32 v228, s9, v246
	v_add_u32_e32 v245, s9, v249
	ds_read_b128 v[194:197], v230
	ds_read_b128 v[198:201], v230 offset:4096
	ds_read_b128 v[202:205], v230 offset:8192
	ds_read_b128 v[206:209], v230 offset:12288
	ds_read_b128 v[210:213], v247
	ds_read_b128 v[214:217], v247 offset:4096
	s_cmp_ge_u32 s13, s19
	s_cbranch_scc1 .Lat_x_nodma
	s_add_u32 s16, s66, 0x100
	s_addc_u32 s17, s67, 0
	s_add_i32 s9, s22, s24
	s_add_i32 s8, s21, s100
	s_mov_b32 m0, s9
	s_nop 0
	global_load_lds_dwordx4 v220, s[14:15]
	s_add_i32 m0, s9, 0x2000
	s_nop 0
	global_load_lds_dwordx4 v221, s[14:15]
	s_mov_b32 m0, s8
	s_nop 0
	global_load_lds_dwordx4 v222, s[66:67]
	s_add_i32 m0, s8, 0x4000
	s_nop 0
	global_load_lds_dwordx4 v222, s[16:17]
	s_add_i32 m0, s8, 0x2000
	s_nop 0
	global_load_lds_dwordx4 v223, s[66:67]
	s_add_i32 m0, s8, 0x6000
	s_nop 0
	global_load_lds_dwordx4 v223, s[16:17]
; #define SBAR() __builtin_amdgcn_sched_barrier(0)
; __device__ __forceinline__ int crow(int r, int hi) { return (r & 3) + 8 * (r >> 2) + 4 * hi; }
; #define PV_STEP(B) do { pv_reads<(B) + 1>(fn, vb); asm volatile("s_waitcnt lgkmcnt(8)" ::: "memory"); SBAR(); pv_mma(o[B], fc, pa0, pa1, pa2, pa3); SBAR(); fc = fn; } while (0)
; __device__ __forceinline__ int crow(int r, int hi) { return (r & 3) + 8 * (r >> 2) + 4 * hi; }
; __device__ __forceinline__ void pv_all(f32x16* o, int vb, bf16x8 pa0, bf16x8 pa1, bf16x8 pa2, bf16x8 pa3) {
;   VFrag fc, fn;
;   pv_reads<0>(fc, vb);
;   PV_STEP(0); PV_STEP(1); PV_STEP(2); PV_STEP(3); PV_STEP(4); PV_STEP(5); PV_STEP(6);
;   asm volatile("s_waitcnt lgkmcnt(0)" ::: "memory"); SBAR(); pv_mma(o[7], fc, pa0, pa1, pa2, pa3);
; }
; __device__ __forceinline__ void attn_body256(const bf16_t* __restrict__ Qb, const bf16_t* __restrict__ Kh, const bf16_t* __restrict__ Vh,
;                                              bf16_t* Ob, int seq, unsigned char* lds, float lam, int MODE, bf16_t* Ab, const float* wsub) {
;     ...
;   for (int j = 0; j < NT; ++j) {
;     const int b = j & 1;
;     f32x16 p0, p1; float mn, alpha; bf16x8 pa0, pa1, pa2, pa3;
;     SBAR(); qkt(p0, p1, (const bf16_t*)(lds + A2_KOFF + b * A2_KBUF), qr, r32, hi);
;     partialSM(p0, p1, m_reg, mn, alpha);
;     if (__any(alpha < 1.f)) { if (hi == 0) al_l[r32] = alpha; asm volatile("s_waitcnt lgkmcnt(0)" ::: "memory");
; #pragma unroll
;       for (int r = 0; r < 16; ++r) { const float a = al_l[crow(r, hi)];
; #pragma unroll
;         for (int d = 0; d < 8; ++d) o[d][r] *= a; } }
;     finishSM(p0, p1, alpha, l_reg, pa0, pa1, pa2, pa3); SBAR();
;     pv_all(o, vb0 + b * A2_VBUF, pa0, pa1, pa2, pa3);
;     asm volatile("s_waitcnt vmcnt(0)" ::: "memory"); __syncthreads();
;     if (j + 2 < NT) A2_DMA(j + 2, b);
.Lat_x_nodma:
	s_mov_b32 s101, s98
	s_mov_b32 s98, s99
	s_mov_b32 s99, s100
	s_mov_b32 s100, s101
	s_add_u32 s14, s14, 0x40000
	s_addc_u32 s15, s15, 0
	s_add_u32 s66, s66, 0x40000
	s_addc_u32 s67, s67, 0
	s_add_i32 s13, s13, 1
	s_cmp_eq_u32 s23, s13
	s_cbranch_scc0 .Lat_x_top
	s_waitcnt lgkmcnt(0)
	s_branch .Lat_epi
.Lat_y_top:
	s_waitcnt lgkmcnt(8)
	v_mfma_f32_16x16x32_bf16 v[2:5], v[146:149], v[130:133], v[2:5]
	v_mfma_f32_16x16x32_bf16 v[6:9], v[146:149], v[134:137], v[6:9]
	v_mfma_f32_16x16x32_bf16 v[2:5], v[150:153], v[138:141], v[2:5]
	v_mfma_f32_16x16x32_bf16 v[6:9], v[150:153], v[142:145], v[6:9]
	ds_read_b64_tr_b16 v[146:147], v244 offset:768
	ds_read_b64_tr_b16 v[148:149], v244 offset:4864
	ds_read_b64_tr_b16 v[150:151], v244 offset:8960
	ds_read_b64_tr_b16 v[152:153], v244 offset:13056
	s_waitcnt lgkmcnt(8)
	v_mfma_f32_16x16x32_bf16 v[10:13], v[154:157], v[130:133], v[10:13]
	v_mfma_f32_16x16x32_bf16 v[14:17], v[154:157], v[134:137], v[14:17]
	v_mfma_f32_16x16x32_bf16 v[10:13], v[158:161], v[138:141], v[10:13]
	v_mfma_f32_16x16x32_bf16 v[14:17], v[158:161], v[142:145], v[14:17]
	ds_read_b64_tr_b16 v[154:155], v244 offset:1024
	ds_read_b64_tr_b16 v[156:157], v244 offset:5120
	ds_read_b64_tr_b16 v[158:159], v244 offset:9216
	ds_read_b64_tr_b16 v[160:161], v244 offset:13312
	s_waitcnt lgkmcnt(8)
	v_mfma_f32_16x16x32_bf16 v[114:117], v[194:197], v[130:133], v[114:117]
	v_mfma_f32_16x16x32_bf16 v[118:121], v[194:197], v[134:137], v[118:121]
	v_mfma_f32_16x16x32_bf16 v[114:117], v[198:201], v[138:141], v[114:117]
	v_mfma_f32_16x16x32_bf16 v[118:121], v[198:201], v[142:145], v[118:121]
	ds_read_b64_tr_b16 v[194:195], v244 offset:1280
	ds_read_b64_tr_b16 v[196:197], v244 offset:5376
	ds_read_b64_tr_b16 v[198:199], v244 offset:9472
	ds_read_b64_tr_b16 v[200:201], v244 offset:13568
	s_waitcnt lgkmcnt(8)
	v_mfma_f32_16x16x32_bf16 v[122:125], v[146:149], v[130:133], v[122:125]
	v_mfma_f32_16x16x32_bf16 v[126:129], v[146:149], v[134:137], v[126:129]
	v_mfma_f32_16x16x32_bf16 v[122:125], v[150:153], v[138:141], v[122:125]
	v_mfma_f32_16x16x32_bf16 v[126:129], v[150:153], v[142:145], v[126:129]
	ds_read_b64_tr_b16 v[146:147], v244 offset:1536
	ds_read_b64_tr_b16 v[148:149], v244 offset:5632
	ds_read_b64_tr_b16 v[150:151], v244 offset:9728
	ds_read_b64_tr_b16 v[152:153], v244 offset:13824
	s_waitcnt lgkmcnt(8)
	v_mfma_f32_16x16x32_bf16 v[98:101], v[154:157], v[130:133], v[98:101]
	v_mfma_f32_16x16x32_bf16 v[102:105], v[154:157], v[134:137], v[102:105]
	v_mfma_f32_16x16x32_bf16 v[98:101], v[158:161], v[138:141], v[98:101]
	v_mfma_f32_16x16x32_bf16 v[102:105], v[158:161], v[142:145], v[102:105]
	ds_read_b64_tr_b16 v[154:155], v244 offset:1792
	ds_read_b64_tr_b16 v[156:157], v244 offset:5888
	ds_read_b64_tr_b16 v[158:159], v244 offset:9984
	ds_read_b64_tr_b16 v[160:161], v244 offset:14080
	s_waitcnt lgkmcnt(8)
	v_mfma_f32_16x16x32_bf16 v[106:109], v[194:197], v[130:133], v[106:109]
	v_mfma_f32_16x16x32_bf16 v[110:113], v[194:197], v[134:137], v[110:113]
	v_mfma_f32_16x16x32_bf16 v[106:109], v[198:201], v[138:141], v[106:109]
	v_mfma_f32_16x16x32_bf16 v[110:113], v[198:201], v[142:145], v[110:113]
	ds_read_b64_tr_b16 v[194:195], v244 offset:16384
	ds_read_b64_tr_b16 v[196:197], v244 offset:20480
	ds_read_b64_tr_b16 v[198:199], v244 offset:24576
	ds_read_b64_tr_b16 v[200:201], v244 offset:28672
	s_waitcnt lgkmcnt(8)
	v_mfma_f32_16x16x32_bf16 v[82:85], v[146:149], v[130:133], v[82:85]
	v_mfma_f32_16x16x32_bf16 v[86:89], v[146:149], v[134:137], v[86:89]
	v_mfma_f32_16x16x32_bf16 v[82:85], v[150:153], v[138:141], v[82:85]
	v_mfma_f32_16x16x32_bf16 v[86:89], v[150:153], v[142:145], v[86:89]
	ds_read_b64_tr_b16 v[146:147], v244 offset:16640
	ds_read_b64_tr_b16 v[148:149], v244 offset:20736
	ds_read_b64_tr_b16 v[150:151], v244 offset:24832
	ds_read_b64_tr_b16 v[152:153], v244 offset:28928
	s_waitcnt lgkmcnt(8)
	v_mfma_f32_16x16x32_bf16 v[90:93], v[154:157], v[130:133], v[90:93]
	v_mfma_f32_16x16x32_bf16 v[94:97], v[154:157], v[134:137], v[94:97]
	v_mfma_f32_16x16x32_bf16 v[90:93], v[158:161], v[138:141], v[90:93]
	v_mfma_f32_16x16x32_bf16 v[94:97], v[158:161], v[142:145], v[94:97]
	ds_read_b64_tr_b16 v[154:155], v244 offset:16896
	ds_read_b64_tr_b16 v[156:157], v244 offset:20992
	ds_read_b64_tr_b16 v[158:159], v244 offset:25088
	ds_read_b64_tr_b16 v[160:161], v244 offset:29184
	s_waitcnt lgkmcnt(8)
; #define SBAR() __builtin_amdgcn_sched_barrier(0)
; #define PV_STEP(B) do { pv_reads<(B) + 1>(fn, vb); asm volatile("s_waitcnt lgkmcnt(8)" ::: "memory"); SBAR(); pv_mma(o[B], fc, pa0, pa1, pa2, pa3); SBAR(); fc = fn; } while (0)
; __device__ __forceinline__ void pv_all(f32x16* o, int vb, bf16x8 pa0, bf16x8 pa1, bf16x8 pa2, bf16x8 pa3) {
;   VFrag fc, fn;
;   pv_reads<0>(fc, vb);
;   PV_STEP(0); PV_STEP(1); PV_STEP(2); PV_STEP(3); PV_STEP(4); PV_STEP(5); PV_STEP(6);
;   asm volatile("s_waitcnt lgkmcnt(0)" ::: "memory"); SBAR(); pv_mma(o[7], fc, pa0, pa1, pa2, pa3);
; }
; __device__ __forceinline__ void attn_body256(const bf16_t* __restrict__ Qb, const bf16_t* __restrict__ Kh, const bf16_t* __restrict__ Vh,
;                                              bf16_t* Ob, int seq, unsigned char* lds, float lam, int MODE, bf16_t* Ab, const float* wsub) {
;     ...
;     pv_all(o, vb0 + b * A2_VBUF, pa0, pa1, pa2, pa3);
;     asm volatile("s_waitcnt vmcnt(0)" ::: "memory"); __syncthreads();
;     if (j + 2 < NT) A2_DMA(j + 2, b);
	v_mfma_f32_16x16x32_bf16 v[66:69], v[194:197], v[130:133], v[66:69]
	v_mfma_f32_16x16x32_bf16 v[70:73], v[194:197], v[134:137], v[70:73]
	v_mfma_f32_16x16x32_bf16 v[66:69], v[198:201], v[138:141], v[66:69]
	v_mfma_f32_16x16x32_bf16 v[70:73], v[198:201], v[142:145], v[70:73]
	ds_read_b64_tr_b16 v[194:195], v244 offset:17152
	ds_read_b64_tr_b16 v[196:197], v244 offset:21248
	ds_read_b64_tr_b16 v[198:199], v244 offset:25344
	ds_read_b64_tr_b16 v[200:201], v244 offset:29440
	s_waitcnt lgkmcnt(8)
	v_mfma_f32_16x16x32_bf16 v[74:77], v[146:149], v[130:133], v[74:77]
	v_mfma_f32_16x16x32_bf16 v[78:81], v[146:149], v[134:137], v[78:81]
	v_mfma_f32_16x16x32_bf16 v[74:77], v[150:153], v[138:141], v[74:77]
	v_mfma_f32_16x16x32_bf16 v[78:81], v[150:153], v[142:145], v[78:81]
	ds_read_b64_tr_b16 v[146:147], v244 offset:17408
	ds_read_b64_tr_b16 v[148:149], v244 offset:21504
	ds_read_b64_tr_b16 v[150:151], v244 offset:25600
	ds_read_b64_tr_b16 v[152:153], v244 offset:29696
	s_waitcnt lgkmcnt(8)
	v_mfma_f32_16x16x32_bf16 v[50:53], v[154:157], v[130:133], v[50:53]
	v_mfma_f32_16x16x32_bf16 v[54:57], v[154:157], v[134:137], v[54:57]
	v_mfma_f32_16x16x32_bf16 v[50:53], v[158:161], v[138:141], v[50:53]
	v_mfma_f32_16x16x32_bf16 v[54:57], v[158:161], v[142:145], v[54:57]
	ds_read_b64_tr_b16 v[154:155], v244 offset:17664
	ds_read_b64_tr_b16 v[156:157], v244 offset:21760
	ds_read_b64_tr_b16 v[158:159], v244 offset:25856
	ds_read_b64_tr_b16 v[160:161], v244 offset:29952
	s_waitcnt lgkmcnt(8)
	v_mfma_f32_16x16x32_bf16 v[58:61], v[194:197], v[130:133], v[58:61]
	v_mfma_f32_16x16x32_bf16 v[62:65], v[194:197], v[134:137], v[62:65]
	v_mfma_f32_16x16x32_bf16 v[58:61], v[198:201], v[138:141], v[58:61]
	v_mfma_f32_16x16x32_bf16 v[62:65], v[198:201], v[142:145], v[62:65]
	ds_read_b64_tr_b16 v[194:195], v244 offset:17920
	ds_read_b64_tr_b16 v[196:197], v244 offset:22016
	ds_read_b64_tr_b16 v[198:199], v244 offset:26112
	ds_read_b64_tr_b16 v[200:201], v244 offset:30208
	s_waitcnt lgkmcnt(8)
	v_mfma_f32_16x16x32_bf16 v[34:37], v[146:149], v[130:133], v[34:37]
	v_mfma_f32_16x16x32_bf16 v[38:41], v[146:149], v[134:137], v[38:41]
	v_mfma_f32_16x16x32_bf16 v[34:37], v[150:153], v[138:141], v[34:37]
	v_mfma_f32_16x16x32_bf16 v[38:41], v[150:153], v[142:145], v[38:41]
	ds_read_b64_tr_b16 v[146:147], v244 offset:18176
	ds_read_b64_tr_b16 v[148:149], v244 offset:22272
	ds_read_b64_tr_b16 v[150:151], v244 offset:26368
	ds_read_b64_tr_b16 v[152:153], v244 offset:30464
	s_waitcnt lgkmcnt(8)
	v_mfma_f32_16x16x32_bf16 v[42:45], v[154:157], v[130:133], v[42:45]
	v_mfma_f32_16x16x32_bf16 v[46:49], v[154:157], v[134:137], v[46:49]
	v_mfma_f32_16x16x32_bf16 v[42:45], v[158:161], v[138:141], v[42:45]
	v_mfma_f32_16x16x32_bf16 v[46:49], v[158:161], v[142:145], v[46:49]
	s_waitcnt lgkmcnt(4)
	v_mfma_f32_16x16x32_bf16 v[18:21], v[194:197], v[130:133], v[18:21]
	v_mfma_f32_16x16x32_bf16 v[22:25], v[194:197], v[134:137], v[22:25]
	v_mfma_f32_16x16x32_bf16 v[18:21], v[198:201], v[138:141], v[18:21]
	v_mfma_f32_16x16x32_bf16 v[22:25], v[198:201], v[142:145], v[22:25]
	s_waitcnt lgkmcnt(0)
	v_mfma_f32_16x16x32_bf16 v[26:29], v[146:149], v[130:133], v[26:29]
	v_mfma_f32_16x16x32_bf16 v[30:33], v[146:149], v[134:137], v[30:33]
	v_mfma_f32_16x16x32_bf16 v[26:29], v[150:153], v[138:141], v[26:29]
	v_mfma_f32_16x16x32_bf16 v[30:33], v[150:153], v[142:145], v[30:33]
	s_cmp_gt_u32 s13, s19
	s_cbranch_scc1 .Lat_y_nodma
	s_sub_u32 s16, s14, 0x40000
	s_subb_u32 s17, s15, 0
	s_add_i32 s9, s22, s24
	s_add_i32 s8, s21, s99
	s_mov_b32 m0, s9
	s_nop 0
	global_load_lds_dwordx4 v220, s[16:17]
	s_add_i32 m0, s9, 0x2000
	s_nop 0
	global_load_lds_dwordx4 v221, s[16:17]
	s_sub_u32 s16, s66, 0x40000
	s_subb_u32 s17, s67, 0
	s_mov_b32 m0, s8
	s_nop 0
	global_load_lds_dwordx4 v222, s[16:17]
	s_add_i32 m0, s8, 0x2000
	s_nop 0
	global_load_lds_dwordx4 v223, s[16:17]
	s_add_u32 s16, s16, 0x100
	s_addc_u32 s17, s17, 0
	s_add_i32 m0, s8, 0x4000
	s_nop 0
	global_load_lds_dwordx4 v222, s[16:17]
	s_add_i32 m0, s8, 0x6000
	s_nop 0
	global_load_lds_dwordx4 v223, s[16:17]

; #define SBAR() __builtin_amdgcn_sched_barrier(0)
; __device__ __forceinline__ int crow(int r, int hi) { return (r & 3) + 8 * (r >> 2) + 4 * hi; }
; __device__ __forceinline__ int crow(int r, int hi) { return (r & 3) + 8 * (r >> 2) + 4 * hi; }
; __device__ __forceinline__ void partialSM(f32x16& p0, f32x16& p1, float& m_reg, float& mn, float& alpha) {
;     ...
;   for (int r = 0; r < 16; ++r) p0[r] = __builtin_amdgcn_exp2f(p0[r]);
; }
; __device__ __forceinline__ void finishSM(f32x16& p0, f32x16& p1, float alpha, float& l_reg, bf16x8& pa0, bf16x8& pa1, bf16x8& pa2, bf16x8& pa3) {
;   for (int r = 0; r < 16; ++r) p1[r] = __builtin_amdgcn_exp2f(p1[r]);
;   float ps = 0; for (int r = 0; r < 16; ++r) ps += p0[r]; for (int r = 0; r < 16; ++r) ps += p1[r];
;   { auto rr = __builtin_amdgcn_permlane32_swap(__float_as_uint(ps), __float_as_uint(ps), false, false);
;     ps = __uint_as_float(rr[0]) + __uint_as_float(rr[1]); }
;   l_reg = l_reg * alpha + ps;
;     ...
;   PK4(p0, 0, pa0); PK4(p0, 8, pa1); PK4(p1, 0, pa2); PK4(p1, 8, pa3);
; __device__ __forceinline__ void attn_body256(const bf16_t* __restrict__ Qb, const bf16_t* __restrict__ Kh, const bf16_t* __restrict__ Vh,
;                                              bf16_t* Ob, int seq, unsigned char* lds, float lam, int MODE, bf16_t* Ab, const float* wsub) {
;     ...
;   for (int j = 0; j < NT; ++j) {
;     const int b = j & 1;
;     f32x16 p0, p1; float mn, alpha; bf16x8 pa0, pa1, pa2, pa3;
;     SBAR(); qkt(p0, p1, (const bf16_t*)(lds + A2_KOFF + b * A2_KBUF), qr, r32, hi);
;     partialSM(p0, p1, m_reg, mn, alpha);
;     if (__any(alpha < 1.f)) { if (hi == 0) al_l[r32] = alpha; asm volatile("s_waitcnt lgkmcnt(0)" ::: "memory");
; #pragma unroll
;       for (int r = 0; r < 16; ++r) { const float a = al_l[crow(r, hi)];
; #pragma unroll
;         for (int d = 0; d < 8; ++d) o[d][r] *= a; } }
;     finishSM(p0, p1, alpha, l_reg, pa0, pa1, pa2, pa3); SBAR();
;     pv_all(o, vb0 + b * A2_VBUF, pa0, pa1, pa2, pa3);
;     asm volatile("s_waitcnt vmcnt(0)" ::: "memory"); __syncthreads();
;     if (j + 2 < NT) A2_DMA(j + 2, b);
.Lat_y_noresc:
	v_exp_f32_e32 v130, v130
	v_exp_f32_e32 v131, v131
	v_exp_f32_e32 v132, v132
	v_exp_f32_e32 v133, v133
	v_exp_f32_e32 v134, v134
	v_exp_f32_e32 v135, v135
	v_exp_f32_e32 v136, v136
	v_exp_f32_e32 v137, v137
	v_exp_f32_e32 v138, v138
	v_exp_f32_e32 v139, v139
	v_exp_f32_e32 v140, v140
	v_exp_f32_e32 v141, v141
	v_exp_f32_e32 v142, v142
	v_exp_f32_e32 v143, v143
	v_exp_f32_e32 v144, v144
	v_exp_f32_e32 v145, v145
	v_exp_f32_e32 v146, v146
	v_exp_f32_e32 v147, v147
	v_exp_f32_e32 v148, v148
	v_exp_f32_e32 v149, v149
	v_exp_f32_e32 v150, v150
	v_exp_f32_e32 v151, v151
	v_exp_f32_e32 v152, v152
	v_exp_f32_e32 v153, v153
	v_exp_f32_e32 v154, v154
	v_exp_f32_e32 v155, v155
	v_exp_f32_e32 v156, v156
	v_exp_f32_e32 v157, v157
	v_exp_f32_e32 v158, v158
	v_exp_f32_e32 v159, v159
	v_exp_f32_e32 v160, v160
	v_exp_f32_e32 v161, v161
	v_add_f32_e32 v194, v130, v131
	v_add_f32_e32 v194, v194, v132
	v_add_f32_e32 v194, v194, v133
	v_add_f32_e32 v194, v194, v138
	v_add_f32_e32 v194, v194, v139
	v_add_f32_e32 v194, v194, v140
	v_add_f32_e32 v194, v194, v141
	v_add_f32_e32 v194, v194, v146
	v_add_f32_e32 v194, v194, v147
	v_add_f32_e32 v194, v194, v148
	v_add_f32_e32 v194, v194, v149
	v_add_f32_e32 v194, v194, v154
	v_add_f32_e32 v194, v194, v155
	v_add_f32_e32 v194, v194, v156
	v_add_f32_e32 v194, v194, v157
	v_add_f32_e32 v195, v134, v135
	v_add_f32_e32 v195, v195, v136
	v_add_f32_e32 v195, v195, v137
	v_add_f32_e32 v195, v195, v142
	v_add_f32_e32 v195, v195, v143
	v_add_f32_e32 v195, v195, v144
	v_add_f32_e32 v195, v195, v145
	v_add_f32_e32 v195, v195, v150
	v_add_f32_e32 v195, v195, v151
	v_add_f32_e32 v195, v195, v152
	v_add_f32_e32 v195, v195, v153
	v_add_f32_e32 v195, v195, v158
	v_add_f32_e32 v195, v195, v159
	v_add_f32_e32 v195, v195, v160
	v_add_f32_e32 v195, v195, v161
	v_add_f32_e32 v250, v250, v194
	v_add_f32_e32 v234, v234, v195
	v_cvt_pk_bf16_f32 v130, v130, v131
	v_cvt_pk_bf16_f32 v131, v132, v133
	v_cvt_pk_bf16_f32 v132, v138, v139
	v_cvt_pk_bf16_f32 v133, v140, v141
	v_cvt_pk_bf16_f32 v134, v134, v135
	v_cvt_pk_bf16_f32 v135, v136, v137
	v_cvt_pk_bf16_f32 v136, v142, v143
	v_cvt_pk_bf16_f32 v137, v144, v145
	v_cvt_pk_bf16_f32 v138, v146, v147
	v_cvt_pk_bf16_f32 v139, v148, v149
	v_cvt_pk_bf16_f32 v140, v154, v155
	v_cvt_pk_bf16_f32 v141, v156, v157
	v_cvt_pk_bf16_f32 v142, v150, v151
	v_cvt_pk_bf16_f32 v143, v152, v153
	v_cvt_pk_bf16_f32 v144, v158, v159
	v_cvt_pk_bf16_f32 v145, v160, v161
	v_add_u32_e32 v244, s98, v248
	ds_read_b64_tr_b16 v[146:147], v244
	ds_read_b64_tr_b16 v[148:149], v244 offset:4096
	ds_read_b64_tr_b16 v[150:151], v244 offset:8192
	ds_read_b64_tr_b16 v[152:153], v244 offset:12288
	ds_read_b64_tr_b16 v[154:155], v244 offset:256
	ds_read_b64_tr_b16 v[156:157], v244 offset:4352
	ds_read_b64_tr_b16 v[158:159], v244 offset:8448
	ds_read_b64_tr_b16 v[160:161], v244 offset:12544
	ds_read_b64_tr_b16 v[194:195], v244 offset:512
	ds_read_b64_tr_b16 v[196:197], v244 offset:4608
	ds_read_b64_tr_b16 v[198:199], v244 offset:8704
	ds_read_b64_tr_b16 v[200:201], v244 offset:12800
	s_waitcnt vmcnt(0)
	s_barrier
	s_mov_b32 s101, s98
	s_mov_b32 s98, s99
	s_mov_b32 s99, s100
	s_mov_b32 s100, s101
	s_add_u32 s14, s14, 0x40000
	s_addc_u32 s15, s15, 0
	s_add_u32 s66, s66, 0x40000
	s_addc_u32 s67, s67, 0
	s_add_i32 s13, s13, 1
	s_cmp_eq_u32 s23, s13
	s_cbranch_scc0 .Lat_y_top
	s_waitcnt lgkmcnt(8)
	v_mfma_f32_16x16x32_bf16 v[2:5], v[146:149], v[130:133], v[2:5]
	v_mfma_f32_16x16x32_bf16 v[6:9], v[146:149], v[134:137], v[6:9]
	v_mfma_f32_16x16x32_bf16 v[2:5], v[150:153], v[138:141], v[2:5]
	v_mfma_f32_16x16x32_bf16 v[6:9], v[150:153], v[142:145], v[6:9]
	ds_read_b64_tr_b16 v[146:147], v244 offset:768
	ds_read_b64_tr_b16 v[148:149], v244 offset:4864
	ds_read_b64_tr_b16 v[150:151], v244 offset:8960
	ds_read_b64_tr_b16 v[152:153], v244 offset:13056
	s_waitcnt lgkmcnt(8)
	v_mfma_f32_16x16x32_bf16 v[10:13], v[154:157], v[130:133], v[10:13]
	v_mfma_f32_16x16x32_bf16 v[14:17], v[154:157], v[134:137], v[14:17]
	v_mfma_f32_16x16x32_bf16 v[10:13], v[158:161], v[138:141], v[10:13]
	v_mfma_f32_16x16x32_bf16 v[14:17], v[158:161], v[142:145], v[14:17]
	ds_read_b64_tr_b16 v[154:155], v244 offset:1024
	ds_read_b64_tr_b16 v[156:157], v244 offset:5120
	ds_read_b64_tr_b16 v[158:159], v244 offset:9216
	ds_read_b64_tr_b16 v[160:161], v244 offset:13312
	s_waitcnt lgkmcnt(8)
	v_mfma_f32_16x16x32_bf16 v[114:117], v[194:197], v[130:133], v[114:117]
	v_mfma_f32_16x16x32_bf16 v[118:121], v[194:197], v[134:137], v[118:121]
	v_mfma_f32_16x16x32_bf16 v[114:117], v[198:201], v[138:141], v[114:117]
	v_mfma_f32_16x16x32_bf16 v[118:121], v[198:201], v[142:145], v[118:121]
	ds_read_b64_tr_b16 v[194:195], v244 offset:1280
	ds_read_b64_tr_b16 v[196:197], v244 offset:5376
	ds_read_b64_tr_b16 v[198:199], v244 offset:9472
	ds_read_b64_tr_b16 v[200:201], v244 offset:13568
	s_waitcnt lgkmcnt(8)
	v_mfma_f32_16x16x32_bf16 v[122:125], v[146:149], v[130:133], v[122:125]
	v_mfma_f32_16x16x32_bf16 v[126:129], v[146:149], v[134:137], v[126:129]
	v_mfma_f32_16x16x32_bf16 v[122:125], v[150:153], v[138:141], v[122:125]
	v_mfma_f32_16x16x32_bf16 v[126:129], v[150:153], v[142:145], v[126:129]
	ds_read_b64_tr_b16 v[146:147], v244 offset:1536
	ds_read_b64_tr_b16 v[148:149], v244 offset:5632
	ds_read_b64_tr_b16 v[150:151], v244 offset:9728
	ds_read_b64_tr_b16 v[152:153], v244 offset:13824
	s_waitcnt lgkmcnt(8)
; #define SBAR() __builtin_amdgcn_sched_barrier(0)
; #define PV_STEP(B) do { pv_reads<(B) + 1>(fn, vb); asm volatile("s_waitcnt lgkmcnt(8)" ::: "memory"); SBAR(); pv_mma(o[B], fc, pa0, pa1, pa2, pa3); SBAR(); fc = fn; } while (0)
; __device__ __forceinline__ void pv_all(f32x16* o, int vb, bf16x8 pa0, bf16x8 pa1, bf16x8 pa2, bf16x8 pa3) {
;   VFrag fc, fn;
;   pv_reads<0>(fc, vb);
;   PV_STEP(0); PV_STEP(1); PV_STEP(2); PV_STEP(3); PV_STEP(4); PV_STEP(5); PV_STEP(6);
;   asm volatile("s_waitcnt lgkmcnt(0)" ::: "memory"); SBAR(); pv_mma(o[7], fc, pa0, pa1, pa2, pa3);
; }
	v_mfma_f32_16x16x32_bf16 v[98:101], v[154:157], v[130:133], v[98:101]
	v_mfma_f32_16x16x32_bf16 v[102:105], v[154:157], v[134:137], v[102:105]
	v_mfma_f32_16x16x32_bf16 v[98:101], v[158:161], v[138:141], v[98:101]
	v_mfma_f32_16x16x32_bf16 v[102:105], v[158:161], v[142:145], v[102:105]
	ds_read_b64_tr_b16 v[154:155], v244 offset:1792
	ds_read_b64_tr_b16 v[156:157], v244 offset:5888
	ds_read_b64_tr_b16 v[158:159], v244 offset:9984
	ds_read_b64_tr_b16 v[160:161], v244 offset:14080
	s_waitcnt lgkmcnt(8)
	v_mfma_f32_16x16x32_bf16 v[106:109], v[194:197], v[130:133], v[106:109]
	v_mfma_f32_16x16x32_bf16 v[110:113], v[194:197], v[134:137], v[110:113]
	v_mfma_f32_16x16x32_bf16 v[106:109], v[198:201], v[138:141], v[106:109]
	v_mfma_f32_16x16x32_bf16 v[110:113], v[198:201], v[142:145], v[110:113]
	ds_read_b64_tr_b16 v[194:195], v244 offset:16384
	ds_read_b64_tr_b16 v[196:197], v244 offset:20480
	ds_read_b64_tr_b16 v[198:199], v244 offset:24576
	ds_read_b64_tr_b16 v[200:201], v244 offset:28672
	s_waitcnt lgkmcnt(8)
	v_mfma_f32_16x16x32_bf16 v[82:85], v[146:149], v[130:133], v[82:85]
	v_mfma_f32_16x16x32_bf16 v[86:89], v[146:149], v[134:137], v[86:89]
	v_mfma_f32_16x16x32_bf16 v[82:85], v[150:153], v[138:141], v[82:85]
	v_mfma_f32_16x16x32_bf16 v[86:89], v[150:153], v[142:145], v[86:89]
	ds_read_b64_tr_b16 v[146:147], v244 offset:16640
	ds_read_b64_tr_b16 v[148:149], v244 offset:20736
	ds_read_b64_tr_b16 v[150:151], v244 offset:24832
	ds_read_b64_tr_b16 v[152:153], v244 offset:28928
	s_waitcnt lgkmcnt(8)
	v_mfma_f32_16x16x32_bf16 v[90:93], v[154:157], v[130:133], v[90:93]
	v_mfma_f32_16x16x32_bf16 v[94:97], v[154:157], v[134:137], v[94:97]
	v_mfma_f32_16x16x32_bf16 v[90:93], v[158:161], v[138:141], v[90:93]
	v_mfma_f32_16x16x32_bf16 v[94:97], v[158:161], v[142:145], v[94:97]
	ds_read_b64_tr_b16 v[154:155], v244 offset:16896
	ds_read_b64_tr_b16 v[156:157], v244 offset:20992
	ds_read_b64_tr_b16 v[158:159], v244 offset:25088
	ds_read_b64_tr_b16 v[160:161], v244 offset:29184
	s_waitcnt lgkmcnt(8)
	v_mfma_f32_16x16x32_bf16 v[66:69], v[194:197], v[130:133], v[66:69]
	v_mfma_f32_16x16x32_bf16 v[70:73], v[194:197], v[134:137], v[70:73]
	v_mfma_f32_16x16x32_bf16 v[66:69], v[198:201], v[138:141], v[66:69]
	v_mfma_f32_16x16x32_bf16 v[70:73], v[198:201], v[142:145], v[70:73]
	ds_read_b64_tr_b16 v[194:195], v244 offset:17152
	ds_read_b64_tr_b16 v[196:197], v244 offset:21248
	ds_read_b64_tr_b16 v[198:199], v244 offset:25344
	ds_read_b64_tr_b16 v[200:201], v244 offset:29440
	s_waitcnt lgkmcnt(8)
	v_mfma_f32_16x16x32_bf16 v[74:77], v[146:149], v[130:133], v[74:77]
	v_mfma_f32_16x16x32_bf16 v[78:81], v[146:149], v[134:137], v[78:81]
	v_mfma_f32_16x16x32_bf16 v[74:77], v[150:153], v[138:141], v[74:77]
	v_mfma_f32_16x16x32_bf16 v[78:81], v[150:153], v[142:145], v[78:81]
	ds_read_b64_tr_b16 v[146:147], v244 offset:17408
	ds_read_b64_tr_b16 v[148:149], v244 offset:21504
	ds_read_b64_tr_b16 v[150:151], v244 offset:25600
	ds_read_b64_tr_b16 v[152:153], v244 offset:29696
	s_waitcnt lgkmcnt(8)
	v_mfma_f32_16x16x32_bf16 v[50:53], v[154:157], v[130:133], v[50:53]
	v_mfma_f32_16x16x32_bf16 v[54:57], v[154:157], v[134:137], v[54:57]
	v_mfma_f32_16x16x32_bf16 v[50:53], v[158:161], v[138:141], v[50:53]
	v_mfma_f32_16x16x32_bf16 v[54:57], v[158:161], v[142:145], v[54:57]
	ds_read_b64_tr_b16 v[154:155], v244 offset:17664
	ds_read_b64_tr_b16 v[156:157], v244 offset:21760
	ds_read_b64_tr_b16 v[158:159], v244 offset:25856
	ds_read_b64_tr_b16 v[160:161], v244 offset:29952
	s_waitcnt lgkmcnt(8)
	v_mfma_f32_16x16x32_bf16 v[58:61], v[194:197], v[130:133], v[58:61]
	v_mfma_f32_16x16x32_bf16 v[62:65], v[194:197], v[134:137], v[62:65]
	v_mfma_f32_16x16x32_bf16 v[58:61], v[198:201], v[138:141], v[58:61]
	v_mfma_f32_16x16x32_bf16 v[62:65], v[198:201], v[142:145], v[62:65]
	ds_read_b64_tr_b16 v[194:195], v244 offset:17920
	ds_read_b64_tr_b16 v[196:197], v244 offset:22016
	ds_read_b64_tr_b16 v[198:199], v244 offset:26112
	ds_read_b64_tr_b16 v[200:201], v244 offset:30208
	s_waitcnt lgkmcnt(8)
	v_mfma_f32_16x16x32_bf16 v[34:37], v[146:149], v[130:133], v[34:37]
	v_mfma_f32_16x16x32_bf16 v[38:41], v[146:149], v[134:137], v[38:41]
	v_mfma_f32_16x16x32_bf16 v[34:37], v[150:153], v[138:141], v[34:37]
	v_mfma_f32_16x16x32_bf16 v[38:41], v[150:153], v[142:145], v[38:41]
	ds_read_b64_tr_b16 v[146:147], v244 offset:18176
	ds_read_b64_tr_b16 v[148:149], v244 offset:22272
	ds_read_b64_tr_b16 v[150:151], v244 offset:26368
	ds_read_b64_tr_b16 v[152:153], v244 offset:30464
	s_waitcnt lgkmcnt(8)
	v_mfma_f32_16x16x32_bf16 v[42:45], v[154:157], v[130:133], v[42:45]
	v_mfma_f32_16x16x32_bf16 v[46:49], v[154:157], v[134:137], v[46:49]
	v_mfma_f32_16x16x32_bf16 v[42:45], v[158:161], v[138:141], v[42:45]
	v_mfma_f32_16x16x32_bf16 v[46:49], v[158:161], v[142:145], v[46:49]
	s_waitcnt lgkmcnt(4)
	v_mfma_f32_16x16x32_bf16 v[18:21], v[194:197], v[130:133], v[18:21]
	v_mfma_f32_16x16x32_bf16 v[22:25], v[194:197], v[134:137], v[22:25]
	v_mfma_f32_16x16x32_bf16 v[18:21], v[198:201], v[138:141], v[18:21]
	v_mfma_f32_16x16x32_bf16 v[22:25], v[198:201], v[142:145], v[22:25]
	s_waitcnt lgkmcnt(0)
	v_mfma_f32_16x16x32_bf16 v[26:29], v[146:149], v[130:133], v[26:29]
	v_mfma_f32_16x16x32_bf16 v[30:33], v[146:149], v[134:137], v[30:33]
	v_mfma_f32_16x16x32_bf16 v[26:29], v[150:153], v[138:141], v[26:29]
	v_mfma_f32_16x16x32_bf16 v[30:33], v[150:153], v[142:145], v[30:33]

; __device__ __forceinline__ void xcd_barrier(const XcdBarrier& b) {
;     asm volatile("s_waitcnt vmcnt(0)" ::: "memory");
;     __syncthreads();
;     if (threadIdx.x == 0) {
;         unsigned* bar = b.bar;
;         __builtin_amdgcn_s_waitcnt(0);
;         unsigned nloc = b.st[0], nx = b.st[1];
;         if (nloc == 0u) { xcd_barrier_complete(bar, b.x, nloc, nx); b.st[0] = nloc; b.st[1] = nx; }
.LBB0_684:
	v_mov_b64_e32 v[210:211], 0x3ff
	v_mov_b64_e32 v[212:213], 0x400
	v_mov_b32_e32 v244, 0x3727c5ac
	v_mov_b32_e32 v245, 0x41b17218
	v_mov_b32_e32 v239, 1
	v_mov_b64_e32 v[242:243], 0x1600
	s_mov_b64 s[66:67], 0x80
	s_getreg_b32 s2, hwreg(HW_REG_XCC_ID, 0, 4)
	s_waitcnt vmcnt(0)
	s_barrier
	s_mov_b64 s[0:1], exec
	v_readlane_b32 s6, v252, 0
	v_readlane_b32 s7, v252, 1
	s_and_b64 s[6:7], s[0:1], s[6:7]
	s_mov_b64 exec, s[6:7]
	s_cbranch_execz .LBB0_736
	v_readlane_b32 s6, v254, 43
	s_waitcnt vmcnt(0) expcnt(0) lgkmcnt(0)
	s_and_b32 s2, s2, 15
	v_mov_b32_e32 v0, s6
	ds_read_b32 v3, v0
	v_readlane_b32 s6, v254, 44
	s_waitcnt lgkmcnt(0)
	v_cmp_ne_u32_e32 vcc, 0, v3
	v_mov_b32_e32 v0, s6
	ds_read_b32 v2, v0
	s_cbranch_vccnz .LBB0_700
	s_mov_b32 s12, 1
	s_branch .LBB0_688
